# static s_setprio 1 for waves 4-7 in MLA attention loop + LDS swizzle
# speedup vs baseline: 1.0011x; 1.0011x over previous
; __device__ __forceinline__ void xcd_barrier(const XcdBarrier& b) {
;     asm volatile("s_waitcnt vmcnt(0)" ::: "memory");
;     __syncthreads();
;     if (threadIdx.x == 0) {
;         unsigned* bar = b.bar;
;         __builtin_amdgcn_s_waitcnt(0);
;         unsigned nloc = b.st[0], nx = b.st[1];
;         if (nloc == 0u) { xcd_barrier_complete(bar, b.x, nloc, nx); b.st[0] = nloc; b.st[1] = nx; }
.LBB0_1206:
	s_setprio 0
	s_waitcnt vmcnt(0)
	s_barrier
	s_and_saveexec_b64 s[0:1], s[96:97]
	v_readlane_b32 s52, v255, 42
	v_readlane_b32 s23, v255, 44
	v_readlane_b32 s51, v255, 41
	v_readlane_b32 s53, v255, 43
	v_readlane_b32 s4, v255, 45
	s_movk_i32 s50, 0x1fff
	s_cbranch_execz .LBB0_1291
	v_readlane_b32 s6, v255, 29
	s_waitcnt vmcnt(0) expcnt(0) lgkmcnt(0)
	s_nop 0
	v_mov_b32_e32 v0, s6
	ds_read_b32 v3, v0
	v_readlane_b32 s6, v255, 30
	s_waitcnt lgkmcnt(0)
	v_cmp_ne_u32_e32 vcc, 0, v3
	v_mov_b32_e32 v0, s6
	ds_read_b32 v2, v0
	s_cbranch_vccnz .LBB0_1255
	s_mov_b32 s30, 1
	s_branch .LBB0_1243

; __device__ __forceinline__ KP fresh_params() { KP p = (KP)__builtin_amdgcn_kernarg_segment_ptr(); asm volatile("" : "+s"(p)); return p; }
; __global__ void __launch_bounds__(512, 2) fwd_mega(Params Pk) {
;     ...
;         for (int slot = bid; slot < 256; slot += G) { KP P = fresh_params();
;             const int h = slot & 3, part = (slot >> 2) & 1, i0 = slot >> 3;
; #pragma unroll 1
;             for (int rep = 0; rep < 2; ++rep) {
;                 const int i = rep ? 63 - i0 : i0, nkb = i + 1, h0 = (nkb + 1) >> 1;
;                 const int kt_lo = part ? 2 * h0 : 0, kt_hi = part ? 2 * nkb : 2 * h0;
;                 attn_block<192>(lds, (const bf16_t*)(P->ws + W_QB) + ((size_t)h * SEQ + i * 128) * 192, (const bf16_t*)(P->ws + W_KB) + (size_t)h * SEQ * 192,
;                                 (const bf16_t*)(P->ws + W_VBT) + (size_t)h * 128 * SEQ, i * 128, kt_lo, kt_hi, 1 << 30, 0.f, 0,
;                                 (bf16_t*)(P->ws + W_OB) + (size_t)part * SEQ * 512, (float*)(P->ws + W_LSEB) + (size_t)part * SEQ * 4, h);
;             }
.LBB0_1210:
	v_readfirstlane_b32 s100, v250
	s_cmp_lt_u32 s100, 0x100
	s_cbranch_scc1 .Lmy_p6_lowprio
	s_setprio 1

; __global__ void __launch_bounds__(512, 2) fwd_mega(Params Pk) {
	.amdhsa_kernel _Z8fwd_mega6Params
		.amdhsa_group_segment_fixed_size 0
		.amdhsa_private_segment_fixed_size 0
		.amdhsa_kernarg_size 504
		.amdhsa_user_sgpr_count 2
		.amdhsa_user_sgpr_dispatch_ptr 0
		.amdhsa_user_sgpr_queue_ptr 0
		.amdhsa_user_sgpr_kernarg_segment_ptr 1
		.amdhsa_user_sgpr_dispatch_id 0
		.amdhsa_user_sgpr_kernarg_preload_length 0
		.amdhsa_user_sgpr_kernarg_preload_offset 0
		.amdhsa_user_sgpr_private_segment_size 0
		.amdhsa_uses_dynamic_stack 0
		.amdhsa_enable_private_segment 0
		.amdhsa_system_sgpr_workgroup_id_x 1
		.amdhsa_system_sgpr_workgroup_id_y 0
		.amdhsa_system_sgpr_workgroup_id_z 0
		.amdhsa_system_sgpr_workgroup_info 0
		.amdhsa_system_vgpr_workitem_id 2
		.amdhsa_next_free_vgpr 256
		.amdhsa_next_free_sgpr 102
		.amdhsa_accum_offset 256
		.amdhsa_reserve_vcc 1
		.amdhsa_float_round_mode_32 0
		.amdhsa_float_round_mode_16_64 0
		.amdhsa_float_denorm_mode_32 3
		.amdhsa_float_denorm_mode_16_64 3
		.amdhsa_dx10_clamp 1
		.amdhsa_ieee_mode 1
		.amdhsa_fp16_overflow 0
		.amdhsa_tg_split 0
		.amdhsa_exception_fp_ieee_invalid_op 0
		.amdhsa_exception_fp_denorm_src 0
		.amdhsa_exception_fp_ieee_div_zero 0
		.amdhsa_exception_fp_ieee_overflow 0
		.amdhsa_exception_fp_ieee_underflow 0
		.amdhsa_exception_fp_ieee_inexact 0
		.amdhsa_exception_int_div_zero 0
	.end_amdhsa_kernel

; __global__ void __launch_bounds__(512, 2) fwd_mega(Params Pk) {
amdhsa.kernels:
  - .agpr_count:     0
    .args:
      - .offset:         0
        .size:           248
        .value_kind:     by_value
      - .offset:         248
        .size:           4
        .value_kind:     hidden_block_count_x
      - .offset:         252
        .size:           4
        .value_kind:     hidden_block_count_y
      - .offset:         256
        .size:           4
        .value_kind:     hidden_block_count_z
      - .offset:         260
        .size:           2
        .value_kind:     hidden_group_size_x
      - .offset:         262
        .size:           2
        .value_kind:     hidden_group_size_y
      - .offset:         264
        .size:           2
        .value_kind:     hidden_group_size_z
      - .offset:         266
        .size:           2
        .value_kind:     hidden_remainder_x
      - .offset:         268
        .size:           2
        .value_kind:     hidden_remainder_y
      - .offset:         270
        .size:           2
        .value_kind:     hidden_remainder_z
      - .offset:         288
        .size:           8
        .value_kind:     hidden_global_offset_x
      - .offset:         296
        .size:           8
        .value_kind:     hidden_global_offset_y
      - .offset:         304
        .size:           8
        .value_kind:     hidden_global_offset_z
      - .offset:         312
        .size:           2
        .value_kind:     hidden_grid_dims
      - .offset:         336
        .size:           8
        .value_kind:     hidden_multigrid_sync_arg
      - .offset:         368
        .size:           4
        .value_kind:     hidden_dynamic_lds_size
    .group_segment_fixed_size: 0
    .kernarg_segment_align: 8
    .kernarg_segment_size: 504
    .language:       OpenCL C
    .language_version:
      - 2
      - 0
    .max_flat_workgroup_size: 512
    .name:           _Z8fwd_mega6Params
    .private_segment_fixed_size: 0
    .sgpr_count:     108
    .sgpr_spill_count: 188
    .symbol:         _Z8fwd_mega6Params.kd
    .uniform_work_group_size: 1
    .uses_dynamic_stack: false
    .vgpr_count:     256
    .vgpr_spill_count: 0
    .wavefront_size: 64
